# s_setprio flips deleted plus ONE static s_setprio 1 for waves 4-7 at kernel entry (younger-half raise)
# baseline (speedup 1.0000x reference)
.LBB0_2:
	s_load_dwordx2 s[22:23], s[68:69], 0xa8
	s_and_b32 s33, s0, 0xffffffc0
	s_cmpk_lt_u32 s33, 0x100
	s_cbranch_scc1 .Lprio_static_done
	s_setprio 1
.Lprio_static_done:
	v_or_b32_e32 v79, s33, v78
	s_movk_i32 s1, 0x1000
	v_cmp_gt_i32_e32 vcc, s1, v79
	s_and_saveexec_b64 s[2:3], vcc
	s_cbranch_execz .LBB0_5
	v_lshl_add_u32 v1, v79, 2, 0
	v_add_u32_e32 v0, 0xfffffe00, v79
	v_add_u32_e32 v1, 0x20000, v1
	s_mov_b64 s[4:5], 0
	v_mov_b32_e32 v2, 0
	s_movk_i32 s1, 0xdff
